# gather epilogue: eight row loads issued together, consumed progressively (one round trip instead of four)
# baseline (speedup 1.0000x reference)
.LBB0_1060:
	v_ashrrev_i32_e32 v4, 11, v132
	v_mul_i32_i24_e32 v4, 0x1800, v4
	v_readlane_b32 s76, v248, 40
	v_ashrrev_i32_e32 v5, 31, v4
	v_readlane_b32 s90, v248, 54
	v_readlane_b32 s91, v248, 55
	v_lshl_add_u64 v[18:19], v[8:9], 2, v[2:3]
	v_add_u32_e32 v132, s62, v132
	v_lshl_add_u64 v[4:5], v[4:5], 2, s[90:91]
	v_lshl_add_u64 v[16:17], v[4:5], 0, v[76:77]
	v_add_co_u32_e32 v20, vcc, s35, v16
	v_readlane_b32 s77, v248, 41
	s_nop 0
	v_addc_co_u32_e32 v21, vcc, 0, v17, vcc
	v_min_i32_e32 v176, 0x7fff, v132
	v_ashrrev_i32_e32 v177, 31, v176
	v_lshlrev_b64 v[178:179], 9, v[176:177]
	v_lshl_or_b32 v178, v128, 2, v178
	v_lshl_add_u64 v[180:181], s[74:75], 0, v[178:179]
	global_load_dword v160, v[180:181], off
	global_load_dword v162, v[180:181], off offset:256
	v_lshlrev_b64 v[180:181], 11, v[176:177]
	v_lshl_add_u64 v[180:181], v[0:1], 0, v[180:181]
	global_load_dwordx4 v[164:167], v[180:181], off
	global_load_dwordx4 v[168:171], v[180:181], off offset:16
	v_lshl_add_u64 v[180:181], s[16:17], 0, v[178:179]
	v_or_b32_e32 v178, 0x100, v178
	v_lshl_add_u64 v[178:179], s[16:17], 0, v[178:179]
	global_load_dword v172, v[180:181], off
	global_load_dword v173, v[178:179], off
	global_load_dwordx4 v[184:187], v[20:21], off
	global_load_dwordx4 v[188:191], v[18:19], off
	global_load_dwordx4 v[192:195], v[20:21], off offset:16
	global_load_dwordx4 v[196:199], v[18:19], off offset:16
	global_load_dwordx4 v[200:203], v[20:21], off offset:32
	global_load_dwordx4 v[204:207], v[18:19], off offset:32
	global_load_dwordx4 v[208:211], v[20:21], off offset:48
	global_load_dwordx4 v[212:215], v[18:19], off offset:48
	v_lshl_add_u64 v[16:17], v[16:17], 0, s[20:21]
	v_cmp_lt_i32_e32 vcc, s36, v132
	s_or_b64 s[18:19], vcc, s[18:19]
	v_readlane_b32 s78, v248, 42
	v_readlane_b32 s79, v248, 43
	v_readlane_b32 s80, v248, 44
	v_readlane_b32 s81, v248, 45
	v_readlane_b32 s82, v248, 46
	v_readlane_b32 s83, v248, 47
	v_readlane_b32 s84, v248, 48
	v_readlane_b32 s85, v248, 49
	v_readlane_b32 s86, v248, 50
	v_readlane_b32 s87, v248, 51
	v_readlane_b32 s88, v248, 52
	v_readlane_b32 s89, v248, 53
	s_waitcnt vmcnt(6)
	v_pk_fma_f32 v[4:5], v[38:39], v[184:185], v[188:189]
	v_pk_fma_f32 v[6:7], v[40:41], v[186:187], v[190:191]
	global_store_dwordx4 v[18:19], v[4:7], off
	v_ashrrev_i32_e32 v161, 31, v160
	v_ashrrev_i32_e32 v163, 31, v162
	v_lshlrev_b64 v[176:177], 2, v[160:161]
	v_lshlrev_b64 v[178:179], 2, v[162:163]
	v_lshl_add_u64 v[180:181], s[54:55], 0, v[176:177]
	v_lshl_add_u64 v[176:177], s[56:57], 0, v[176:177]
	v_lshl_add_u64 v[182:183], s[54:55], 0, v[178:179]
	v_lshl_add_u64 v[178:179], s[56:57], 0, v[178:179]
	global_load_dword v174, v[176:177], off
	global_load_dword v175, v[178:179], off
	global_load_dword v161, v[180:181], off
	global_load_dword v163, v[182:183], off
	s_waitcnt vmcnt(9)
	v_pk_fma_f32 v[8:9], v[34:35], v[192:193], v[196:197]
	v_pk_fma_f32 v[10:11], v[36:37], v[194:195], v[198:199]
	global_store_dwordx4 v[18:19], v[8:11], off offset:16
	s_waitcnt vmcnt(8)
	v_pk_fma_f32 v[12:13], v[28:29], v[200:201], v[204:205]
	v_pk_fma_f32 v[14:15], v[30:31], v[202:203], v[206:207]
	global_store_dwordx4 v[18:19], v[12:15], off offset:32
	s_waitcnt vmcnt(7)
	v_pk_fma_f32 v[216:217], v[26:27], v[208:209], v[212:213]
	v_pk_fma_f32 v[218:219], v[32:33], v[210:211], v[214:215]
	global_store_dwordx4 v[18:19], v[216:219], off offset:48
	s_waitcnt vmcnt(3)
	s_andn2_b64 exec, exec, s[18:19]
	s_cbranch_execz .LBB0_1067
